# pool_unroll: 16-row window also gets B fragments two k-steps ahead (third set in borrowed base registers, restored after)
# speedup vs baseline: 1.0074x; 1.0074x over previous
.LBB0_332:
	s_or_b64 exec, exec, s[6:7]
	s_waitcnt lgkmcnt(0)
	global_load_dwordx4 v[82:85], v[144:145], off offset:512
	global_load_dwordx4 v[86:89], v[146:147], off offset:512
	global_load_dwordx4 v[90:93], v[148:149], off offset:512
	global_load_dwordx4 v[94:97], v[150:151], off offset:512
	global_load_dwordx4 v[112:115], v[144:145], off offset:1024
	global_load_dwordx4 v[116:119], v[146:147], off offset:1024
	global_load_dwordx4 v[122:125], v[148:149], off offset:1024
	global_load_dwordx4 v[126:129], v[150:151], off offset:1024
	v_or_b32_e32 v2, s28, v1
	v_min_u32_e32 v3, 15, v2
	v_add_u32_e32 v3, 1, v3
	v_cvt_f32_ubyte0_e32 v3, v3
	v_div_scale_f32 v4, s[6:7], v3, v3, 1.0
	v_rcp_f32_e32 v5, v4
	s_ashr_i32 s8, s30, 6
	s_mul_i32 s10, s8, 15
	v_cmp_lt_u32_e64 s[6:7], s41, v2
	v_fma_f32 v6, -v4, v5, 1.0
	v_fmac_f32_e32 v5, v6, v5
	v_div_scale_f32 v6, vcc, 1.0, v3, 1.0
	v_mul_f32_e32 v7, v6, v5
	v_fma_f32 v8, -v4, v7, v6
	v_fmac_f32_e32 v7, v8, v5
	v_fma_f32 v4, -v4, v7, v6
	v_div_fmas_f32 v4, v4, v5, v7
	v_div_fixup_f32 v159, v4, v3, 1.0
	s_ashr_i32 s11, s10, 31
	v_add_u32_e32 v2, 0xfffff80f, v2
	v_mov_b32_e32 v3, v155
	v_lshl_add_u64 v[2:3], v[2:3], 0, s[10:11]
	v_lshlrev_b64 v[2:3], 11, v[2:3]
	v_lshl_add_u64 v[2:3], s[70:71], 0, v[2:3]
	v_mov_b32_e32 v163, v155
	v_lshl_add_u64 v[2:3], v[2:3], 0, v[162:163]
	v_lshl_add_u64 v[192:193], v[2:3], 0, s[16:17]
	v_mov_b32_e32 v2, 0
	s_mov_b32 s49, 0
	s_mov_b64 s[10:11], 0
	v_mov_b32_e32 v3, v2
	v_mov_b32_e32 v4, v2
	v_mov_b32_e32 v5, v2
	v_mov_b32_e32 v6, v2
	v_mov_b32_e32 v7, v2
	v_mov_b32_e32 v8, v2
	v_mov_b32_e32 v9, v2
	v_mov_b32_e32 v10, v2
	v_mov_b32_e32 v11, v2
	v_mov_b32_e32 v12, v2
	v_mov_b32_e32 v13, v2
	v_mov_b32_e32 v14, v2
	v_mov_b32_e32 v15, v2
	v_mov_b32_e32 v16, v2
	v_mov_b32_e32 v17, v2
	v_mov_b32_e32 v18, v2
	v_mov_b32_e32 v19, v2
	v_mov_b32_e32 v20, v2
	v_mov_b32_e32 v21, v2
	v_mov_b32_e32 v22, v2
	v_mov_b32_e32 v23, v2
	v_mov_b32_e32 v24, v2
	v_mov_b32_e32 v25, v2
	v_mov_b32_e32 v26, v2
	v_mov_b32_e32 v27, v2
	v_mov_b32_e32 v28, v2
	v_mov_b32_e32 v29, v2
	v_mov_b32_e32 v30, v2
	v_mov_b32_e32 v31, v2
	v_mov_b32_e32 v32, v2
	v_mov_b32_e32 v33, v2
	v_mov_b32_e32 v34, v2
	v_mov_b32_e32 v35, v2
	v_mov_b32_e32 v36, v2
	v_mov_b32_e32 v37, v2
	v_mov_b32_e32 v38, v2
	v_mov_b32_e32 v39, v2
	v_mov_b32_e32 v40, v2
	v_mov_b32_e32 v41, v2
	v_mov_b32_e32 v42, v2
	v_mov_b32_e32 v43, v2
	v_mov_b32_e32 v44, v2
	v_mov_b32_e32 v45, v2
	v_mov_b32_e32 v46, v2
	v_mov_b32_e32 v47, v2
	v_mov_b32_e32 v48, v2
	v_mov_b32_e32 v49, v2
	v_mov_b32_e32 v50, v2
	v_mov_b32_e32 v51, v2
	v_mov_b32_e32 v52, v2
	v_mov_b32_e32 v53, v2
	v_mov_b32_e32 v54, v2
	v_mov_b32_e32 v55, v2
	v_mov_b32_e32 v56, v2
	v_mov_b32_e32 v57, v2
	v_mov_b32_e32 v58, v2
	v_mov_b32_e32 v59, v2
	v_mov_b32_e32 v60, v2
	v_mov_b32_e32 v61, v2
	v_mov_b32_e32 v62, v2
	v_mov_b32_e32 v63, v2
	v_mov_b32_e32 v64, v2
	v_mov_b32_e32 v65, v2
	s_mov_b32 s50, 0x3f80
	s_mov_b32 s51, 0x3f800000
	v_lshl_add_u32 v163, v197, 1, v214
	ds_read_b128 v[222:225], v163 offset:4080
	ds_read_b128 v[226:229], v163 offset:3808
	ds_read_b128 v[230:233], v163 offset:3536
	ds_read_b128 v[234:237], v163 offset:3264
	ds_read_b128 v[238:241], v163 offset:2992
	ds_read_b128 v[242:245], v163 offset:2720
	ds_read_b128 v[248:251], v163 offset:2448
	ds_read_b128 v[252:255], v163 offset:2176
	s_waitcnt lgkmcnt(7)
	v_lshlrev_b32_e32 v98, 16, v222
	v_and_b32_e32 v99, 0xffff0000, v222
	v_lshlrev_b32_e32 v100, 16, v223
	v_and_b32_e32 v101, 0xffff0000, v223
	v_lshlrev_b32_e32 v102, 16, v224
	v_and_b32_e32 v103, 0xffff0000, v224
	v_lshlrev_b32_e32 v104, 16, v225
	v_and_b32_e32 v105, 0xffff0000, v225
	v_mov_b64_e32 v[106:107], v[98:99]
	v_mov_b64_e32 v[108:109], v[100:101]
	v_mov_b64_e32 v[218:219], v[102:103]
	v_mov_b64_e32 v[220:221], v[104:105]
	ds_read_b128 v[222:225], v163 offset:1904
	s_waitcnt lgkmcnt(7)
	v_dot2c_f32_bf16 v106, s50, v226
	v_dot2c_f32_bf16 v107, s51, v226
	v_dot2c_f32_bf16 v108, s50, v227
	v_dot2c_f32_bf16 v109, s51, v227
	v_dot2c_f32_bf16 v218, s50, v228
	v_dot2c_f32_bf16 v219, s51, v228
	v_dot2c_f32_bf16 v220, s50, v229
	v_dot2c_f32_bf16 v221, s51, v229
	ds_read_b128 v[226:229], v163 offset:1632
	s_waitcnt lgkmcnt(7)
	v_dot2c_f32_bf16 v106, s50, v230
	v_dot2c_f32_bf16 v107, s51, v230
	v_dot2c_f32_bf16 v108, s50, v231
	v_dot2c_f32_bf16 v109, s51, v231
	v_dot2c_f32_bf16 v218, s50, v232
	v_dot2c_f32_bf16 v219, s51, v232
	v_dot2c_f32_bf16 v220, s50, v233
	v_dot2c_f32_bf16 v221, s51, v233
	ds_read_b128 v[230:233], v163 offset:1360
	s_waitcnt lgkmcnt(7)
	v_dot2c_f32_bf16 v106, s50, v234
	v_dot2c_f32_bf16 v107, s51, v234
	v_dot2c_f32_bf16 v108, s50, v235
	v_dot2c_f32_bf16 v109, s51, v235
	v_dot2c_f32_bf16 v218, s50, v236
	v_dot2c_f32_bf16 v219, s51, v236
	v_dot2c_f32_bf16 v220, s50, v237
	v_dot2c_f32_bf16 v221, s51, v237
	ds_read_b128 v[234:237], v163 offset:1088
	s_waitcnt lgkmcnt(7)
	v_dot2c_f32_bf16 v106, s50, v238
	v_dot2c_f32_bf16 v107, s51, v238
	v_dot2c_f32_bf16 v108, s50, v239
	v_dot2c_f32_bf16 v109, s51, v239
	v_dot2c_f32_bf16 v218, s50, v240
	v_dot2c_f32_bf16 v219, s51, v240
	v_dot2c_f32_bf16 v220, s50, v241
	v_dot2c_f32_bf16 v221, s51, v241
	ds_read_b128 v[238:241], v163 offset:816
	s_waitcnt lgkmcnt(7)
	v_dot2c_f32_bf16 v106, s50, v242
	v_dot2c_f32_bf16 v107, s51, v242
	v_dot2c_f32_bf16 v108, s50, v243
	v_dot2c_f32_bf16 v109, s51, v243
	v_dot2c_f32_bf16 v218, s50, v244
	v_dot2c_f32_bf16 v219, s51, v244
	v_dot2c_f32_bf16 v220, s50, v245
	v_dot2c_f32_bf16 v221, s51, v245
	ds_read_b128 v[242:245], v163 offset:544
	s_waitcnt lgkmcnt(7)
	v_dot2c_f32_bf16 v106, s50, v248
	v_dot2c_f32_bf16 v107, s51, v248
	v_dot2c_f32_bf16 v108, s50, v249
	v_dot2c_f32_bf16 v109, s51, v249
	v_dot2c_f32_bf16 v218, s50, v250
	v_dot2c_f32_bf16 v219, s51, v250
	v_dot2c_f32_bf16 v220, s50, v251
	v_dot2c_f32_bf16 v221, s51, v251
	ds_read_b128 v[248:251], v163 offset:272
	s_waitcnt lgkmcnt(7)
	v_dot2c_f32_bf16 v106, s50, v252
	v_dot2c_f32_bf16 v107, s51, v252
	v_dot2c_f32_bf16 v108, s50, v253
	v_dot2c_f32_bf16 v109, s51, v253
	v_dot2c_f32_bf16 v218, s50, v254
	v_dot2c_f32_bf16 v219, s51, v254
	v_dot2c_f32_bf16 v220, s50, v255
	v_dot2c_f32_bf16 v221, s51, v255
	ds_read_b128 v[252:255], v163 offset:0
	s_waitcnt lgkmcnt(7)
	v_dot2c_f32_bf16 v106, s50, v222
	v_dot2c_f32_bf16 v107, s51, v222
	v_dot2c_f32_bf16 v108, s50, v223
	v_dot2c_f32_bf16 v109, s51, v223
	v_dot2c_f32_bf16 v218, s50, v224
	v_dot2c_f32_bf16 v219, s51, v224
	v_dot2c_f32_bf16 v220, s50, v225
	v_dot2c_f32_bf16 v221, s51, v225
	ds_read_b128 v[222:225], v163 offset:4112
	s_waitcnt lgkmcnt(7)
	v_dot2c_f32_bf16 v106, s50, v226
	v_dot2c_f32_bf16 v107, s51, v226
	v_dot2c_f32_bf16 v108, s50, v227
	v_dot2c_f32_bf16 v109, s51, v227
	v_dot2c_f32_bf16 v218, s50, v228
	v_dot2c_f32_bf16 v219, s51, v228
	v_dot2c_f32_bf16 v220, s50, v229
	v_dot2c_f32_bf16 v221, s51, v229
	ds_read_b128 v[226:229], v163 offset:3840
	s_waitcnt lgkmcnt(7)
	v_dot2c_f32_bf16 v106, s50, v230
	v_dot2c_f32_bf16 v107, s51, v230
	v_dot2c_f32_bf16 v108, s50, v231
	v_dot2c_f32_bf16 v109, s51, v231
	v_dot2c_f32_bf16 v218, s50, v232
	v_dot2c_f32_bf16 v219, s51, v232
	v_dot2c_f32_bf16 v220, s50, v233
	v_dot2c_f32_bf16 v221, s51, v233
	ds_read_b128 v[230:233], v163 offset:3568
	s_waitcnt lgkmcnt(7)
	v_dot2c_f32_bf16 v106, s50, v234
	v_dot2c_f32_bf16 v107, s51, v234
	v_dot2c_f32_bf16 v108, s50, v235
	v_dot2c_f32_bf16 v109, s51, v235
	v_dot2c_f32_bf16 v218, s50, v236
	v_dot2c_f32_bf16 v219, s51, v236
	v_dot2c_f32_bf16 v220, s50, v237
	v_dot2c_f32_bf16 v221, s51, v237
	ds_read_b128 v[234:237], v163 offset:3296
	s_waitcnt lgkmcnt(7)
	v_dot2c_f32_bf16 v106, s50, v238
	v_dot2c_f32_bf16 v107, s51, v238
	v_dot2c_f32_bf16 v108, s50, v239
	v_dot2c_f32_bf16 v109, s51, v239
	v_dot2c_f32_bf16 v218, s50, v240
	v_dot2c_f32_bf16 v219, s51, v240
	v_dot2c_f32_bf16 v220, s50, v241
	v_dot2c_f32_bf16 v221, s51, v241
	ds_read_b128 v[238:241], v163 offset:3024
	s_waitcnt lgkmcnt(7)
	v_dot2c_f32_bf16 v106, s50, v242
	v_dot2c_f32_bf16 v107, s51, v242
	v_dot2c_f32_bf16 v108, s50, v243
	v_dot2c_f32_bf16 v109, s51, v243
	v_dot2c_f32_bf16 v218, s50, v244
	v_dot2c_f32_bf16 v219, s51, v244
	v_dot2c_f32_bf16 v220, s50, v245
	v_dot2c_f32_bf16 v221, s51, v245
	ds_read_b128 v[242:245], v163 offset:2752
	s_waitcnt lgkmcnt(7)
	v_dot2c_f32_bf16 v106, s50, v248
	v_dot2c_f32_bf16 v107, s51, v248
	v_dot2c_f32_bf16 v108, s50, v249
	v_dot2c_f32_bf16 v109, s51, v249
	v_dot2c_f32_bf16 v218, s50, v250
	v_dot2c_f32_bf16 v219, s51, v250
	v_dot2c_f32_bf16 v220, s50, v251
	v_dot2c_f32_bf16 v221, s51, v251
	ds_read_b128 v[248:251], v163 offset:2480
	s_waitcnt lgkmcnt(7)
	v_dot2c_f32_bf16 v106, s50, v252
	v_dot2c_f32_bf16 v107, s51, v252
	v_dot2c_f32_bf16 v108, s50, v253
	v_dot2c_f32_bf16 v109, s51, v253
	v_dot2c_f32_bf16 v218, s50, v254
	v_dot2c_f32_bf16 v219, s51, v254
	v_dot2c_f32_bf16 v220, s50, v255
	v_dot2c_f32_bf16 v221, s51, v255
	ds_read_b128 v[252:255], v163 offset:2208
	v_fma_f32 v106, v159, v106, -v98
	v_fma_f32 v107, v159, v107, -v99
	v_fma_f32 v108, v159, v108, -v100
	v_fma_f32 v109, v159, v109, -v101
	v_fma_f32 v218, v159, v218, -v102
	v_fma_f32 v219, v159, v219, -v103
	v_fma_f32 v220, v159, v220, -v104
	v_fma_f32 v221, v159, v221, -v105
	v_cvt_pk_bf16_f32 v106, v106, v107
	v_cvt_pk_bf16_f32 v107, v108, v109
	v_cvt_pk_bf16_f32 v108, v218, v219
	v_cvt_pk_bf16_f32 v109, v220, v221
	s_and_saveexec_b64 s[28:29], s[6:7]
	s_cbranch_execz .Lpu0_0
	global_store_dwordx4 v[192:193], v[98:101], off offset:0
	global_store_dwordx4 v[192:193], v[102:105], off offset:16
.Lpu0_0:
	s_or_b64 exec, exec, s[28:29]
	s_waitcnt vmcnt(8)
	v_mfma_f32_32x32x16_bf16 v[2:17], v[106:109], v[70:73], v[2:17]
	v_mfma_f32_32x32x16_bf16 v[18:33], v[106:109], v[74:77], v[18:33]
	v_mfma_f32_32x32x16_bf16 v[34:49], v[106:109], v[78:81], v[34:49]
	v_mfma_f32_32x32x16_bf16 v[50:65], v[106:109], v[66:69], v[50:65]
	global_load_dwordx4 v[70:73], v[144:145], off offset:1536
	global_load_dwordx4 v[74:77], v[146:147], off offset:1536
	global_load_dwordx4 v[78:81], v[148:149], off offset:1536
	global_load_dwordx4 v[66:69], v[150:151], off offset:1536
	s_waitcnt lgkmcnt(7)
	v_lshlrev_b32_e32 v98, 16, v222
	v_and_b32_e32 v99, 0xffff0000, v222
	v_lshlrev_b32_e32 v100, 16, v223
	v_and_b32_e32 v101, 0xffff0000, v223
	v_lshlrev_b32_e32 v102, 16, v224
	v_and_b32_e32 v103, 0xffff0000, v224
	v_lshlrev_b32_e32 v104, 16, v225
	v_and_b32_e32 v105, 0xffff0000, v225
	v_mov_b64_e32 v[106:107], v[98:99]
	v_mov_b64_e32 v[108:109], v[100:101]
	v_mov_b64_e32 v[218:219], v[102:103]
	v_mov_b64_e32 v[220:221], v[104:105]
	ds_read_b128 v[222:225], v163 offset:1936
	s_waitcnt lgkmcnt(7)
	v_dot2c_f32_bf16 v106, s50, v226
	v_dot2c_f32_bf16 v107, s51, v226
	v_dot2c_f32_bf16 v108, s50, v227
	v_dot2c_f32_bf16 v109, s51, v227
	v_dot2c_f32_bf16 v218, s50, v228
	v_dot2c_f32_bf16 v219, s51, v228
	v_dot2c_f32_bf16 v220, s50, v229
	v_dot2c_f32_bf16 v221, s51, v229
	ds_read_b128 v[226:229], v163 offset:1664
	s_waitcnt lgkmcnt(7)
	v_dot2c_f32_bf16 v106, s50, v230
	v_dot2c_f32_bf16 v107, s51, v230
	v_dot2c_f32_bf16 v108, s50, v231
	v_dot2c_f32_bf16 v109, s51, v231
	v_dot2c_f32_bf16 v218, s50, v232
	v_dot2c_f32_bf16 v219, s51, v232
	v_dot2c_f32_bf16 v220, s50, v233
	v_dot2c_f32_bf16 v221, s51, v233
	ds_read_b128 v[230:233], v163 offset:1392
	s_waitcnt lgkmcnt(7)
	v_dot2c_f32_bf16 v106, s50, v234
	v_dot2c_f32_bf16 v107, s51, v234
	v_dot2c_f32_bf16 v108, s50, v235
	v_dot2c_f32_bf16 v109, s51, v235
	v_dot2c_f32_bf16 v218, s50, v236
	v_dot2c_f32_bf16 v219, s51, v236
	v_dot2c_f32_bf16 v220, s50, v237
	v_dot2c_f32_bf16 v221, s51, v237
	ds_read_b128 v[234:237], v163 offset:1120
	s_waitcnt lgkmcnt(7)
	v_dot2c_f32_bf16 v106, s50, v238
	v_dot2c_f32_bf16 v107, s51, v238
	v_dot2c_f32_bf16 v108, s50, v239
	v_dot2c_f32_bf16 v109, s51, v239
	v_dot2c_f32_bf16 v218, s50, v240
	v_dot2c_f32_bf16 v219, s51, v240
	v_dot2c_f32_bf16 v220, s50, v241
	v_dot2c_f32_bf16 v221, s51, v241
	ds_read_b128 v[238:241], v163 offset:848
	s_waitcnt lgkmcnt(7)
	v_dot2c_f32_bf16 v106, s50, v242
	v_dot2c_f32_bf16 v107, s51, v242
	v_dot2c_f32_bf16 v108, s50, v243
	v_dot2c_f32_bf16 v109, s51, v243
	v_dot2c_f32_bf16 v218, s50, v244
	v_dot2c_f32_bf16 v219, s51, v244
	v_dot2c_f32_bf16 v220, s50, v245
	v_dot2c_f32_bf16 v221, s51, v245
	ds_read_b128 v[242:245], v163 offset:576
	s_waitcnt lgkmcnt(7)
	v_dot2c_f32_bf16 v106, s50, v248
	v_dot2c_f32_bf16 v107, s51, v248
	v_dot2c_f32_bf16 v108, s50, v249
	v_dot2c_f32_bf16 v109, s51, v249
	v_dot2c_f32_bf16 v218, s50, v250
	v_dot2c_f32_bf16 v219, s51, v250
	v_dot2c_f32_bf16 v220, s50, v251
	v_dot2c_f32_bf16 v221, s51, v251
	ds_read_b128 v[248:251], v163 offset:304
	s_waitcnt lgkmcnt(7)
	v_dot2c_f32_bf16 v106, s50, v252
	v_dot2c_f32_bf16 v107, s51, v252
	v_dot2c_f32_bf16 v108, s50, v253
	v_dot2c_f32_bf16 v109, s51, v253
	v_dot2c_f32_bf16 v218, s50, v254
	v_dot2c_f32_bf16 v219, s51, v254
	v_dot2c_f32_bf16 v220, s50, v255
	v_dot2c_f32_bf16 v221, s51, v255
	ds_read_b128 v[252:255], v163 offset:32
	s_waitcnt lgkmcnt(7)
	v_dot2c_f32_bf16 v106, s50, v222
	v_dot2c_f32_bf16 v107, s51, v222
	v_dot2c_f32_bf16 v108, s50, v223
	v_dot2c_f32_bf16 v109, s51, v223
	v_dot2c_f32_bf16 v218, s50, v224
	v_dot2c_f32_bf16 v219, s51, v224
	v_dot2c_f32_bf16 v220, s50, v225
	v_dot2c_f32_bf16 v221, s51, v225
	ds_read_b128 v[222:225], v163 offset:4144
	s_waitcnt lgkmcnt(7)
	v_dot2c_f32_bf16 v106, s50, v226
	v_dot2c_f32_bf16 v107, s51, v226
	v_dot2c_f32_bf16 v108, s50, v227
	v_dot2c_f32_bf16 v109, s51, v227
	v_dot2c_f32_bf16 v218, s50, v228
	v_dot2c_f32_bf16 v219, s51, v228
	v_dot2c_f32_bf16 v220, s50, v229
	v_dot2c_f32_bf16 v221, s51, v229
	ds_read_b128 v[226:229], v163 offset:3872
	s_waitcnt lgkmcnt(7)
	v_dot2c_f32_bf16 v106, s50, v230
	v_dot2c_f32_bf16 v107, s51, v230
	v_dot2c_f32_bf16 v108, s50, v231
	v_dot2c_f32_bf16 v109, s51, v231
	v_dot2c_f32_bf16 v218, s50, v232
	v_dot2c_f32_bf16 v219, s51, v232
	v_dot2c_f32_bf16 v220, s50, v233
	v_dot2c_f32_bf16 v221, s51, v233
	ds_read_b128 v[230:233], v163 offset:3600
	s_waitcnt lgkmcnt(7)
	v_dot2c_f32_bf16 v106, s50, v234
	v_dot2c_f32_bf16 v107, s51, v234
	v_dot2c_f32_bf16 v108, s50, v235
	v_dot2c_f32_bf16 v109, s51, v235
	v_dot2c_f32_bf16 v218, s50, v236
	v_dot2c_f32_bf16 v219, s51, v236
	v_dot2c_f32_bf16 v220, s50, v237
	v_dot2c_f32_bf16 v221, s51, v237
	ds_read_b128 v[234:237], v163 offset:3328
	s_waitcnt lgkmcnt(7)
	v_dot2c_f32_bf16 v106, s50, v238
	v_dot2c_f32_bf16 v107, s51, v238
	v_dot2c_f32_bf16 v108, s50, v239
	v_dot2c_f32_bf16 v109, s51, v239
	v_dot2c_f32_bf16 v218, s50, v240
	v_dot2c_f32_bf16 v219, s51, v240
	v_dot2c_f32_bf16 v220, s50, v241
	v_dot2c_f32_bf16 v221, s51, v241
	ds_read_b128 v[238:241], v163 offset:3056
	s_waitcnt lgkmcnt(7)
	v_dot2c_f32_bf16 v106, s50, v242
	v_dot2c_f32_bf16 v107, s51, v242
	v_dot2c_f32_bf16 v108, s50, v243
	v_dot2c_f32_bf16 v109, s51, v243
	v_dot2c_f32_bf16 v218, s50, v244
	v_dot2c_f32_bf16 v219, s51, v244
	v_dot2c_f32_bf16 v220, s50, v245
	v_dot2c_f32_bf16 v221, s51, v245
	ds_read_b128 v[242:245], v163 offset:2784
	s_waitcnt lgkmcnt(7)
	v_dot2c_f32_bf16 v106, s50, v248
	v_dot2c_f32_bf16 v107, s51, v248
	v_dot2c_f32_bf16 v108, s50, v249
	v_dot2c_f32_bf16 v109, s51, v249
	v_dot2c_f32_bf16 v218, s50, v250
	v_dot2c_f32_bf16 v219, s51, v250
	v_dot2c_f32_bf16 v220, s50, v251
	v_dot2c_f32_bf16 v221, s51, v251
	ds_read_b128 v[248:251], v163 offset:2512
	s_waitcnt lgkmcnt(7)
	v_dot2c_f32_bf16 v106, s50, v252
	v_dot2c_f32_bf16 v107, s51, v252
	v_dot2c_f32_bf16 v108, s50, v253
	v_dot2c_f32_bf16 v109, s51, v253
	v_dot2c_f32_bf16 v218, s50, v254
	v_dot2c_f32_bf16 v219, s51, v254
	v_dot2c_f32_bf16 v220, s50, v255
	v_dot2c_f32_bf16 v221, s51, v255
	ds_read_b128 v[252:255], v163 offset:2240
	v_fma_f32 v106, v159, v106, -v98
	v_fma_f32 v107, v159, v107, -v99
	v_fma_f32 v108, v159, v108, -v100
	v_fma_f32 v109, v159, v109, -v101
	v_fma_f32 v218, v159, v218, -v102
	v_fma_f32 v219, v159, v219, -v103
	v_fma_f32 v220, v159, v220, -v104
	v_fma_f32 v221, v159, v221, -v105
	v_cvt_pk_bf16_f32 v106, v106, v107
	v_cvt_pk_bf16_f32 v107, v108, v109
	v_cvt_pk_bf16_f32 v108, v218, v219
	v_cvt_pk_bf16_f32 v109, v220, v221
	s_and_saveexec_b64 s[28:29], s[6:7]
	s_cbranch_execz .Lpu0_1
	global_store_dwordx4 v[192:193], v[98:101], off offset:64
	global_store_dwordx4 v[192:193], v[102:105], off offset:80
.Lpu0_1:
	s_or_b64 exec, exec, s[28:29]
	s_waitcnt vmcnt(8)
	v_mfma_f32_32x32x16_bf16 v[2:17], v[106:109], v[82:85], v[2:17]
	v_mfma_f32_32x32x16_bf16 v[18:33], v[106:109], v[86:89], v[18:33]
	v_mfma_f32_32x32x16_bf16 v[34:49], v[106:109], v[90:93], v[34:49]
	v_mfma_f32_32x32x16_bf16 v[50:65], v[106:109], v[94:97], v[50:65]
	global_load_dwordx4 v[82:85], v[144:145], off offset:2048
	global_load_dwordx4 v[86:89], v[146:147], off offset:2048
	global_load_dwordx4 v[90:93], v[148:149], off offset:2048
	global_load_dwordx4 v[94:97], v[150:151], off offset:2048
	s_waitcnt lgkmcnt(7)
	v_lshlrev_b32_e32 v98, 16, v222
	v_and_b32_e32 v99, 0xffff0000, v222
	v_lshlrev_b32_e32 v100, 16, v223
	v_and_b32_e32 v101, 0xffff0000, v223
	v_lshlrev_b32_e32 v102, 16, v224
	v_and_b32_e32 v103, 0xffff0000, v224
	v_lshlrev_b32_e32 v104, 16, v225
	v_and_b32_e32 v105, 0xffff0000, v225
	v_mov_b64_e32 v[106:107], v[98:99]
	v_mov_b64_e32 v[108:109], v[100:101]
	v_mov_b64_e32 v[218:219], v[102:103]
	v_mov_b64_e32 v[220:221], v[104:105]
	ds_read_b128 v[222:225], v163 offset:1968
	s_waitcnt lgkmcnt(7)
	v_dot2c_f32_bf16 v106, s50, v226
	v_dot2c_f32_bf16 v107, s51, v226
	v_dot2c_f32_bf16 v108, s50, v227
	v_dot2c_f32_bf16 v109, s51, v227
	v_dot2c_f32_bf16 v218, s50, v228
	v_dot2c_f32_bf16 v219, s51, v228
	v_dot2c_f32_bf16 v220, s50, v229
	v_dot2c_f32_bf16 v221, s51, v229
	ds_read_b128 v[226:229], v163 offset:1696
	s_waitcnt lgkmcnt(7)
	v_dot2c_f32_bf16 v106, s50, v230
	v_dot2c_f32_bf16 v107, s51, v230
	v_dot2c_f32_bf16 v108, s50, v231
	v_dot2c_f32_bf16 v109, s51, v231
	v_dot2c_f32_bf16 v218, s50, v232
	v_dot2c_f32_bf16 v219, s51, v232
	v_dot2c_f32_bf16 v220, s50, v233
	v_dot2c_f32_bf16 v221, s51, v233
	ds_read_b128 v[230:233], v163 offset:1424
	s_waitcnt lgkmcnt(7)
	v_dot2c_f32_bf16 v106, s50, v234
	v_dot2c_f32_bf16 v107, s51, v234
	v_dot2c_f32_bf16 v108, s50, v235
	v_dot2c_f32_bf16 v109, s51, v235
	v_dot2c_f32_bf16 v218, s50, v236
	v_dot2c_f32_bf16 v219, s51, v236
	v_dot2c_f32_bf16 v220, s50, v237
	v_dot2c_f32_bf16 v221, s51, v237
	ds_read_b128 v[234:237], v163 offset:1152
	s_waitcnt lgkmcnt(7)
	v_dot2c_f32_bf16 v106, s50, v238
	v_dot2c_f32_bf16 v107, s51, v238
	v_dot2c_f32_bf16 v108, s50, v239
	v_dot2c_f32_bf16 v109, s51, v239
	v_dot2c_f32_bf16 v218, s50, v240
	v_dot2c_f32_bf16 v219, s51, v240
	v_dot2c_f32_bf16 v220, s50, v241
	v_dot2c_f32_bf16 v221, s51, v241
	ds_read_b128 v[238:241], v163 offset:880
	s_waitcnt lgkmcnt(7)
	v_dot2c_f32_bf16 v106, s50, v242
	v_dot2c_f32_bf16 v107, s51, v242
	v_dot2c_f32_bf16 v108, s50, v243
	v_dot2c_f32_bf16 v109, s51, v243
	v_dot2c_f32_bf16 v218, s50, v244
	v_dot2c_f32_bf16 v219, s51, v244
	v_dot2c_f32_bf16 v220, s50, v245
	v_dot2c_f32_bf16 v221, s51, v245
	ds_read_b128 v[242:245], v163 offset:608
	s_waitcnt lgkmcnt(7)
	v_dot2c_f32_bf16 v106, s50, v248
	v_dot2c_f32_bf16 v107, s51, v248
	v_dot2c_f32_bf16 v108, s50, v249
	v_dot2c_f32_bf16 v109, s51, v249
	v_dot2c_f32_bf16 v218, s50, v250
	v_dot2c_f32_bf16 v219, s51, v250
	v_dot2c_f32_bf16 v220, s50, v251
	v_dot2c_f32_bf16 v221, s51, v251
	ds_read_b128 v[248:251], v163 offset:336
	s_waitcnt lgkmcnt(7)
	v_dot2c_f32_bf16 v106, s50, v252
	v_dot2c_f32_bf16 v107, s51, v252
	v_dot2c_f32_bf16 v108, s50, v253
	v_dot2c_f32_bf16 v109, s51, v253
	v_dot2c_f32_bf16 v218, s50, v254
	v_dot2c_f32_bf16 v219, s51, v254
	v_dot2c_f32_bf16 v220, s50, v255
	v_dot2c_f32_bf16 v221, s51, v255
	ds_read_b128 v[252:255], v163 offset:64
	s_waitcnt lgkmcnt(7)
	v_dot2c_f32_bf16 v106, s50, v222
	v_dot2c_f32_bf16 v107, s51, v222
	v_dot2c_f32_bf16 v108, s50, v223
	v_dot2c_f32_bf16 v109, s51, v223
	v_dot2c_f32_bf16 v218, s50, v224
	v_dot2c_f32_bf16 v219, s51, v224
	v_dot2c_f32_bf16 v220, s50, v225
	v_dot2c_f32_bf16 v221, s51, v225
	ds_read_b128 v[222:225], v163 offset:4176
	s_waitcnt lgkmcnt(7)
	v_dot2c_f32_bf16 v106, s50, v226
	v_dot2c_f32_bf16 v107, s51, v226
	v_dot2c_f32_bf16 v108, s50, v227
	v_dot2c_f32_bf16 v109, s51, v227
	v_dot2c_f32_bf16 v218, s50, v228
	v_dot2c_f32_bf16 v219, s51, v228
	v_dot2c_f32_bf16 v220, s50, v229
	v_dot2c_f32_bf16 v221, s51, v229
	ds_read_b128 v[226:229], v163 offset:3904
	s_waitcnt lgkmcnt(7)
	v_dot2c_f32_bf16 v106, s50, v230
	v_dot2c_f32_bf16 v107, s51, v230
	v_dot2c_f32_bf16 v108, s50, v231
	v_dot2c_f32_bf16 v109, s51, v231
	v_dot2c_f32_bf16 v218, s50, v232
	v_dot2c_f32_bf16 v219, s51, v232
	v_dot2c_f32_bf16 v220, s50, v233
	v_dot2c_f32_bf16 v221, s51, v233
	ds_read_b128 v[230:233], v163 offset:3632
	s_waitcnt lgkmcnt(7)
	v_dot2c_f32_bf16 v106, s50, v234
	v_dot2c_f32_bf16 v107, s51, v234
	v_dot2c_f32_bf16 v108, s50, v235
	v_dot2c_f32_bf16 v109, s51, v235
	v_dot2c_f32_bf16 v218, s50, v236
	v_dot2c_f32_bf16 v219, s51, v236
	v_dot2c_f32_bf16 v220, s50, v237
	v_dot2c_f32_bf16 v221, s51, v237
	ds_read_b128 v[234:237], v163 offset:3360
	s_waitcnt lgkmcnt(7)
	v_dot2c_f32_bf16 v106, s50, v238
	v_dot2c_f32_bf16 v107, s51, v238
	v_dot2c_f32_bf16 v108, s50, v239
	v_dot2c_f32_bf16 v109, s51, v239
	v_dot2c_f32_bf16 v218, s50, v240
	v_dot2c_f32_bf16 v219, s51, v240
	v_dot2c_f32_bf16 v220, s50, v241
	v_dot2c_f32_bf16 v221, s51, v241
	ds_read_b128 v[238:241], v163 offset:3088
	s_waitcnt lgkmcnt(7)
	v_dot2c_f32_bf16 v106, s50, v242
	v_dot2c_f32_bf16 v107, s51, v242
	v_dot2c_f32_bf16 v108, s50, v243
	v_dot2c_f32_bf16 v109, s51, v243
	v_dot2c_f32_bf16 v218, s50, v244
	v_dot2c_f32_bf16 v219, s51, v244
	v_dot2c_f32_bf16 v220, s50, v245
	v_dot2c_f32_bf16 v221, s51, v245
	ds_read_b128 v[242:245], v163 offset:2816
	s_waitcnt lgkmcnt(7)
	v_dot2c_f32_bf16 v106, s50, v248
	v_dot2c_f32_bf16 v107, s51, v248
	v_dot2c_f32_bf16 v108, s50, v249
	v_dot2c_f32_bf16 v109, s51, v249
	v_dot2c_f32_bf16 v218, s50, v250
	v_dot2c_f32_bf16 v219, s51, v250
	v_dot2c_f32_bf16 v220, s50, v251
	v_dot2c_f32_bf16 v221, s51, v251
	ds_read_b128 v[248:251], v163 offset:2544
	s_waitcnt lgkmcnt(7)
	v_dot2c_f32_bf16 v106, s50, v252
	v_dot2c_f32_bf16 v107, s51, v252
	v_dot2c_f32_bf16 v108, s50, v253
	v_dot2c_f32_bf16 v109, s51, v253
	v_dot2c_f32_bf16 v218, s50, v254
	v_dot2c_f32_bf16 v219, s51, v254
	v_dot2c_f32_bf16 v220, s50, v255
	v_dot2c_f32_bf16 v221, s51, v255
	ds_read_b128 v[252:255], v163 offset:2272
	v_fma_f32 v106, v159, v106, -v98
	v_fma_f32 v107, v159, v107, -v99
	v_fma_f32 v108, v159, v108, -v100
	v_fma_f32 v109, v159, v109, -v101
	v_fma_f32 v218, v159, v218, -v102
	v_fma_f32 v219, v159, v219, -v103
	v_fma_f32 v220, v159, v220, -v104
	v_fma_f32 v221, v159, v221, -v105
	v_cvt_pk_bf16_f32 v106, v106, v107
	v_cvt_pk_bf16_f32 v107, v108, v109
	v_cvt_pk_bf16_f32 v108, v218, v219
	v_cvt_pk_bf16_f32 v109, v220, v221
	s_and_saveexec_b64 s[28:29], s[6:7]
	s_cbranch_execz .Lpu0_2
	global_store_dwordx4 v[192:193], v[98:101], off offset:128
	global_store_dwordx4 v[192:193], v[102:105], off offset:144
.Lpu0_2:
	s_or_b64 exec, exec, s[28:29]
	s_waitcnt vmcnt(8)
	v_mfma_f32_32x32x16_bf16 v[2:17], v[106:109], v[112:115], v[2:17]
	v_mfma_f32_32x32x16_bf16 v[18:33], v[106:109], v[116:119], v[18:33]
	v_mfma_f32_32x32x16_bf16 v[34:49], v[106:109], v[122:125], v[34:49]
	v_mfma_f32_32x32x16_bf16 v[50:65], v[106:109], v[126:129], v[50:65]
	global_load_dwordx4 v[112:115], v[144:145], off offset:2560
	global_load_dwordx4 v[116:119], v[146:147], off offset:2560
	global_load_dwordx4 v[122:125], v[148:149], off offset:2560
	global_load_dwordx4 v[126:129], v[150:151], off offset:2560
	s_waitcnt lgkmcnt(7)
	v_lshlrev_b32_e32 v98, 16, v222
	v_and_b32_e32 v99, 0xffff0000, v222
	v_lshlrev_b32_e32 v100, 16, v223
	v_and_b32_e32 v101, 0xffff0000, v223
	v_lshlrev_b32_e32 v102, 16, v224
	v_and_b32_e32 v103, 0xffff0000, v224
	v_lshlrev_b32_e32 v104, 16, v225
	v_and_b32_e32 v105, 0xffff0000, v225
	v_mov_b64_e32 v[106:107], v[98:99]
	v_mov_b64_e32 v[108:109], v[100:101]
	v_mov_b64_e32 v[218:219], v[102:103]
	v_mov_b64_e32 v[220:221], v[104:105]
	ds_read_b128 v[222:225], v163 offset:2000
	s_waitcnt lgkmcnt(7)
	v_dot2c_f32_bf16 v106, s50, v226
	v_dot2c_f32_bf16 v107, s51, v226
	v_dot2c_f32_bf16 v108, s50, v227
	v_dot2c_f32_bf16 v109, s51, v227
	v_dot2c_f32_bf16 v218, s50, v228
	v_dot2c_f32_bf16 v219, s51, v228
	v_dot2c_f32_bf16 v220, s50, v229
	v_dot2c_f32_bf16 v221, s51, v229
	ds_read_b128 v[226:229], v163 offset:1728
	s_waitcnt lgkmcnt(7)
	v_dot2c_f32_bf16 v106, s50, v230
	v_dot2c_f32_bf16 v107, s51, v230
	v_dot2c_f32_bf16 v108, s50, v231
	v_dot2c_f32_bf16 v109, s51, v231
	v_dot2c_f32_bf16 v218, s50, v232
	v_dot2c_f32_bf16 v219, s51, v232
	v_dot2c_f32_bf16 v220, s50, v233
	v_dot2c_f32_bf16 v221, s51, v233
	ds_read_b128 v[230:233], v163 offset:1456
	s_waitcnt lgkmcnt(7)
	v_dot2c_f32_bf16 v106, s50, v234
	v_dot2c_f32_bf16 v107, s51, v234
	v_dot2c_f32_bf16 v108, s50, v235
	v_dot2c_f32_bf16 v109, s51, v235
	v_dot2c_f32_bf16 v218, s50, v236
	v_dot2c_f32_bf16 v219, s51, v236
	v_dot2c_f32_bf16 v220, s50, v237
	v_dot2c_f32_bf16 v221, s51, v237
	ds_read_b128 v[234:237], v163 offset:1184
	s_waitcnt lgkmcnt(7)
	v_dot2c_f32_bf16 v106, s50, v238
	v_dot2c_f32_bf16 v107, s51, v238
	v_dot2c_f32_bf16 v108, s50, v239
	v_dot2c_f32_bf16 v109, s51, v239
	v_dot2c_f32_bf16 v218, s50, v240
	v_dot2c_f32_bf16 v219, s51, v240
	v_dot2c_f32_bf16 v220, s50, v241
	v_dot2c_f32_bf16 v221, s51, v241
	ds_read_b128 v[238:241], v163 offset:912
	s_waitcnt lgkmcnt(7)
	v_dot2c_f32_bf16 v106, s50, v242
	v_dot2c_f32_bf16 v107, s51, v242
	v_dot2c_f32_bf16 v108, s50, v243
	v_dot2c_f32_bf16 v109, s51, v243
	v_dot2c_f32_bf16 v218, s50, v244
	v_dot2c_f32_bf16 v219, s51, v244
	v_dot2c_f32_bf16 v220, s50, v245
	v_dot2c_f32_bf16 v221, s51, v245
	ds_read_b128 v[242:245], v163 offset:640
	s_waitcnt lgkmcnt(7)
	v_dot2c_f32_bf16 v106, s50, v248
	v_dot2c_f32_bf16 v107, s51, v248
	v_dot2c_f32_bf16 v108, s50, v249
	v_dot2c_f32_bf16 v109, s51, v249
	v_dot2c_f32_bf16 v218, s50, v250
	v_dot2c_f32_bf16 v219, s51, v250
	v_dot2c_f32_bf16 v220, s50, v251
	v_dot2c_f32_bf16 v221, s51, v251
	ds_read_b128 v[248:251], v163 offset:368
	s_waitcnt lgkmcnt(7)
	v_dot2c_f32_bf16 v106, s50, v252
	v_dot2c_f32_bf16 v107, s51, v252
	v_dot2c_f32_bf16 v108, s50, v253
	v_dot2c_f32_bf16 v109, s51, v253
	v_dot2c_f32_bf16 v218, s50, v254
	v_dot2c_f32_bf16 v219, s51, v254
	v_dot2c_f32_bf16 v220, s50, v255
	v_dot2c_f32_bf16 v221, s51, v255
	ds_read_b128 v[252:255], v163 offset:96
	s_waitcnt lgkmcnt(7)
	v_dot2c_f32_bf16 v106, s50, v222
	v_dot2c_f32_bf16 v107, s51, v222
	v_dot2c_f32_bf16 v108, s50, v223
	v_dot2c_f32_bf16 v109, s51, v223
	v_dot2c_f32_bf16 v218, s50, v224
	v_dot2c_f32_bf16 v219, s51, v224
	v_dot2c_f32_bf16 v220, s50, v225
	v_dot2c_f32_bf16 v221, s51, v225
	ds_read_b128 v[222:225], v163 offset:4208
	s_waitcnt lgkmcnt(7)
	v_dot2c_f32_bf16 v106, s50, v226
	v_dot2c_f32_bf16 v107, s51, v226
	v_dot2c_f32_bf16 v108, s50, v227
	v_dot2c_f32_bf16 v109, s51, v227
	v_dot2c_f32_bf16 v218, s50, v228
	v_dot2c_f32_bf16 v219, s51, v228
	v_dot2c_f32_bf16 v220, s50, v229
	v_dot2c_f32_bf16 v221, s51, v229
	ds_read_b128 v[226:229], v163 offset:3936
	s_waitcnt lgkmcnt(7)
	v_dot2c_f32_bf16 v106, s50, v230
	v_dot2c_f32_bf16 v107, s51, v230
	v_dot2c_f32_bf16 v108, s50, v231
	v_dot2c_f32_bf16 v109, s51, v231
	v_dot2c_f32_bf16 v218, s50, v232
	v_dot2c_f32_bf16 v219, s51, v232
	v_dot2c_f32_bf16 v220, s50, v233
	v_dot2c_f32_bf16 v221, s51, v233
	ds_read_b128 v[230:233], v163 offset:3664
	s_waitcnt lgkmcnt(7)
	v_dot2c_f32_bf16 v106, s50, v234
	v_dot2c_f32_bf16 v107, s51, v234
	v_dot2c_f32_bf16 v108, s50, v235
	v_dot2c_f32_bf16 v109, s51, v235
	v_dot2c_f32_bf16 v218, s50, v236
	v_dot2c_f32_bf16 v219, s51, v236
	v_dot2c_f32_bf16 v220, s50, v237
	v_dot2c_f32_bf16 v221, s51, v237
	ds_read_b128 v[234:237], v163 offset:3392
	s_waitcnt lgkmcnt(7)
	v_dot2c_f32_bf16 v106, s50, v238
	v_dot2c_f32_bf16 v107, s51, v238
	v_dot2c_f32_bf16 v108, s50, v239
	v_dot2c_f32_bf16 v109, s51, v239
	v_dot2c_f32_bf16 v218, s50, v240
	v_dot2c_f32_bf16 v219, s51, v240
	v_dot2c_f32_bf16 v220, s50, v241
	v_dot2c_f32_bf16 v221, s51, v241
	ds_read_b128 v[238:241], v163 offset:3120
	s_waitcnt lgkmcnt(7)
	v_dot2c_f32_bf16 v106, s50, v242
	v_dot2c_f32_bf16 v107, s51, v242
	v_dot2c_f32_bf16 v108, s50, v243
	v_dot2c_f32_bf16 v109, s51, v243
	v_dot2c_f32_bf16 v218, s50, v244
	v_dot2c_f32_bf16 v219, s51, v244
	v_dot2c_f32_bf16 v220, s50, v245
	v_dot2c_f32_bf16 v221, s51, v245
	ds_read_b128 v[242:245], v163 offset:2848
	s_waitcnt lgkmcnt(7)
	v_dot2c_f32_bf16 v106, s50, v248
	v_dot2c_f32_bf16 v107, s51, v248
	v_dot2c_f32_bf16 v108, s50, v249
	v_dot2c_f32_bf16 v109, s51, v249
	v_dot2c_f32_bf16 v218, s50, v250
	v_dot2c_f32_bf16 v219, s51, v250
	v_dot2c_f32_bf16 v220, s50, v251
	v_dot2c_f32_bf16 v221, s51, v251
	ds_read_b128 v[248:251], v163 offset:2576
	s_waitcnt lgkmcnt(7)
	v_dot2c_f32_bf16 v106, s50, v252
	v_dot2c_f32_bf16 v107, s51, v252
	v_dot2c_f32_bf16 v108, s50, v253
	v_dot2c_f32_bf16 v109, s51, v253
	v_dot2c_f32_bf16 v218, s50, v254
	v_dot2c_f32_bf16 v219, s51, v254
	v_dot2c_f32_bf16 v220, s50, v255
	v_dot2c_f32_bf16 v221, s51, v255
	ds_read_b128 v[252:255], v163 offset:2304
	v_fma_f32 v106, v159, v106, -v98
	v_fma_f32 v107, v159, v107, -v99
	v_fma_f32 v108, v159, v108, -v100
	v_fma_f32 v109, v159, v109, -v101
	v_fma_f32 v218, v159, v218, -v102
	v_fma_f32 v219, v159, v219, -v103
	v_fma_f32 v220, v159, v220, -v104
	v_fma_f32 v221, v159, v221, -v105
	v_cvt_pk_bf16_f32 v106, v106, v107
	v_cvt_pk_bf16_f32 v107, v108, v109
	v_cvt_pk_bf16_f32 v108, v218, v219
	v_cvt_pk_bf16_f32 v109, v220, v221
	s_and_saveexec_b64 s[28:29], s[6:7]
	s_cbranch_execz .Lpu0_3
	global_store_dwordx4 v[192:193], v[98:101], off offset:192
	global_store_dwordx4 v[192:193], v[102:105], off offset:208
.Lpu0_3:
	s_or_b64 exec, exec, s[28:29]
	s_waitcnt vmcnt(8)
	v_mfma_f32_32x32x16_bf16 v[2:17], v[106:109], v[70:73], v[2:17]
	v_mfma_f32_32x32x16_bf16 v[18:33], v[106:109], v[74:77], v[18:33]
	v_mfma_f32_32x32x16_bf16 v[34:49], v[106:109], v[78:81], v[34:49]
	v_mfma_f32_32x32x16_bf16 v[50:65], v[106:109], v[66:69], v[50:65]
	global_load_dwordx4 v[70:73], v[144:145], off offset:3072
	global_load_dwordx4 v[74:77], v[146:147], off offset:3072
	global_load_dwordx4 v[78:81], v[148:149], off offset:3072
	global_load_dwordx4 v[66:69], v[150:151], off offset:3072
	s_waitcnt lgkmcnt(7)
	v_lshlrev_b32_e32 v98, 16, v222
	v_and_b32_e32 v99, 0xffff0000, v222
	v_lshlrev_b32_e32 v100, 16, v223
	v_and_b32_e32 v101, 0xffff0000, v223
	v_lshlrev_b32_e32 v102, 16, v224
	v_and_b32_e32 v103, 0xffff0000, v224
	v_lshlrev_b32_e32 v104, 16, v225
	v_and_b32_e32 v105, 0xffff0000, v225
	v_mov_b64_e32 v[106:107], v[98:99]
	v_mov_b64_e32 v[108:109], v[100:101]
	v_mov_b64_e32 v[218:219], v[102:103]
	v_mov_b64_e32 v[220:221], v[104:105]
	ds_read_b128 v[222:225], v163 offset:2032
	s_waitcnt lgkmcnt(7)
	v_dot2c_f32_bf16 v106, s50, v226
	v_dot2c_f32_bf16 v107, s51, v226
	v_dot2c_f32_bf16 v108, s50, v227
	v_dot2c_f32_bf16 v109, s51, v227
	v_dot2c_f32_bf16 v218, s50, v228
	v_dot2c_f32_bf16 v219, s51, v228
	v_dot2c_f32_bf16 v220, s50, v229
	v_dot2c_f32_bf16 v221, s51, v229
	ds_read_b128 v[226:229], v163 offset:1760
	s_waitcnt lgkmcnt(7)
	v_dot2c_f32_bf16 v106, s50, v230
	v_dot2c_f32_bf16 v107, s51, v230
	v_dot2c_f32_bf16 v108, s50, v231
	v_dot2c_f32_bf16 v109, s51, v231
	v_dot2c_f32_bf16 v218, s50, v232
	v_dot2c_f32_bf16 v219, s51, v232
	v_dot2c_f32_bf16 v220, s50, v233
	v_dot2c_f32_bf16 v221, s51, v233
	ds_read_b128 v[230:233], v163 offset:1488
	s_waitcnt lgkmcnt(7)
	v_dot2c_f32_bf16 v106, s50, v234
	v_dot2c_f32_bf16 v107, s51, v234
	v_dot2c_f32_bf16 v108, s50, v235
	v_dot2c_f32_bf16 v109, s51, v235
	v_dot2c_f32_bf16 v218, s50, v236
	v_dot2c_f32_bf16 v219, s51, v236
	v_dot2c_f32_bf16 v220, s50, v237
	v_dot2c_f32_bf16 v221, s51, v237
	ds_read_b128 v[234:237], v163 offset:1216
	s_waitcnt lgkmcnt(7)
	v_dot2c_f32_bf16 v106, s50, v238
	v_dot2c_f32_bf16 v107, s51, v238
	v_dot2c_f32_bf16 v108, s50, v239
	v_dot2c_f32_bf16 v109, s51, v239
	v_dot2c_f32_bf16 v218, s50, v240
	v_dot2c_f32_bf16 v219, s51, v240
	v_dot2c_f32_bf16 v220, s50, v241
	v_dot2c_f32_bf16 v221, s51, v241
	ds_read_b128 v[238:241], v163 offset:944
	s_waitcnt lgkmcnt(7)
	v_dot2c_f32_bf16 v106, s50, v242
	v_dot2c_f32_bf16 v107, s51, v242
	v_dot2c_f32_bf16 v108, s50, v243
	v_dot2c_f32_bf16 v109, s51, v243
	v_dot2c_f32_bf16 v218, s50, v244
	v_dot2c_f32_bf16 v219, s51, v244
	v_dot2c_f32_bf16 v220, s50, v245
	v_dot2c_f32_bf16 v221, s51, v245
	ds_read_b128 v[242:245], v163 offset:672
	s_waitcnt lgkmcnt(7)
	v_dot2c_f32_bf16 v106, s50, v248
	v_dot2c_f32_bf16 v107, s51, v248
	v_dot2c_f32_bf16 v108, s50, v249
	v_dot2c_f32_bf16 v109, s51, v249
	v_dot2c_f32_bf16 v218, s50, v250
	v_dot2c_f32_bf16 v219, s51, v250
	v_dot2c_f32_bf16 v220, s50, v251
	v_dot2c_f32_bf16 v221, s51, v251
	ds_read_b128 v[248:251], v163 offset:400
	s_waitcnt lgkmcnt(7)
	v_dot2c_f32_bf16 v106, s50, v252
	v_dot2c_f32_bf16 v107, s51, v252
	v_dot2c_f32_bf16 v108, s50, v253
	v_dot2c_f32_bf16 v109, s51, v253
	v_dot2c_f32_bf16 v218, s50, v254
	v_dot2c_f32_bf16 v219, s51, v254
	v_dot2c_f32_bf16 v220, s50, v255
	v_dot2c_f32_bf16 v221, s51, v255
	ds_read_b128 v[252:255], v163 offset:128
	s_waitcnt lgkmcnt(7)
	v_dot2c_f32_bf16 v106, s50, v222
	v_dot2c_f32_bf16 v107, s51, v222
	v_dot2c_f32_bf16 v108, s50, v223
	v_dot2c_f32_bf16 v109, s51, v223
	v_dot2c_f32_bf16 v218, s50, v224
	v_dot2c_f32_bf16 v219, s51, v224
	v_dot2c_f32_bf16 v220, s50, v225
	v_dot2c_f32_bf16 v221, s51, v225
	ds_read_b128 v[222:225], v163 offset:4240
	s_waitcnt lgkmcnt(7)
	v_dot2c_f32_bf16 v106, s50, v226
	v_dot2c_f32_bf16 v107, s51, v226
	v_dot2c_f32_bf16 v108, s50, v227
	v_dot2c_f32_bf16 v109, s51, v227
	v_dot2c_f32_bf16 v218, s50, v228
	v_dot2c_f32_bf16 v219, s51, v228
	v_dot2c_f32_bf16 v220, s50, v229
	v_dot2c_f32_bf16 v221, s51, v229
	ds_read_b128 v[226:229], v163 offset:3968
	s_waitcnt lgkmcnt(7)
	v_dot2c_f32_bf16 v106, s50, v230
	v_dot2c_f32_bf16 v107, s51, v230
	v_dot2c_f32_bf16 v108, s50, v231
	v_dot2c_f32_bf16 v109, s51, v231
	v_dot2c_f32_bf16 v218, s50, v232
	v_dot2c_f32_bf16 v219, s51, v232
	v_dot2c_f32_bf16 v220, s50, v233
	v_dot2c_f32_bf16 v221, s51, v233
	ds_read_b128 v[230:233], v163 offset:3696
	s_waitcnt lgkmcnt(7)
	v_dot2c_f32_bf16 v106, s50, v234
	v_dot2c_f32_bf16 v107, s51, v234
	v_dot2c_f32_bf16 v108, s50, v235
	v_dot2c_f32_bf16 v109, s51, v235
	v_dot2c_f32_bf16 v218, s50, v236
	v_dot2c_f32_bf16 v219, s51, v236
	v_dot2c_f32_bf16 v220, s50, v237
	v_dot2c_f32_bf16 v221, s51, v237
	ds_read_b128 v[234:237], v163 offset:3424
	s_waitcnt lgkmcnt(7)
	v_dot2c_f32_bf16 v106, s50, v238
	v_dot2c_f32_bf16 v107, s51, v238
	v_dot2c_f32_bf16 v108, s50, v239
	v_dot2c_f32_bf16 v109, s51, v239
	v_dot2c_f32_bf16 v218, s50, v240
	v_dot2c_f32_bf16 v219, s51, v240
	v_dot2c_f32_bf16 v220, s50, v241
	v_dot2c_f32_bf16 v221, s51, v241
	ds_read_b128 v[238:241], v163 offset:3152
	s_waitcnt lgkmcnt(7)
	v_dot2c_f32_bf16 v106, s50, v242
	v_dot2c_f32_bf16 v107, s51, v242
	v_dot2c_f32_bf16 v108, s50, v243
	v_dot2c_f32_bf16 v109, s51, v243
	v_dot2c_f32_bf16 v218, s50, v244
	v_dot2c_f32_bf16 v219, s51, v244
	v_dot2c_f32_bf16 v220, s50, v245
	v_dot2c_f32_bf16 v221, s51, v245
	ds_read_b128 v[242:245], v163 offset:2880
	s_waitcnt lgkmcnt(7)
	v_dot2c_f32_bf16 v106, s50, v248
	v_dot2c_f32_bf16 v107, s51, v248
	v_dot2c_f32_bf16 v108, s50, v249
	v_dot2c_f32_bf16 v109, s51, v249
	v_dot2c_f32_bf16 v218, s50, v250
	v_dot2c_f32_bf16 v219, s51, v250
	v_dot2c_f32_bf16 v220, s50, v251
	v_dot2c_f32_bf16 v221, s51, v251
	ds_read_b128 v[248:251], v163 offset:2608
	s_waitcnt lgkmcnt(7)
	v_dot2c_f32_bf16 v106, s50, v252
	v_dot2c_f32_bf16 v107, s51, v252
	v_dot2c_f32_bf16 v108, s50, v253
	v_dot2c_f32_bf16 v109, s51, v253
	v_dot2c_f32_bf16 v218, s50, v254
	v_dot2c_f32_bf16 v219, s51, v254
	v_dot2c_f32_bf16 v220, s50, v255
	v_dot2c_f32_bf16 v221, s51, v255
	ds_read_b128 v[252:255], v163 offset:2336
	v_fma_f32 v106, v159, v106, -v98
	v_fma_f32 v107, v159, v107, -v99
	v_fma_f32 v108, v159, v108, -v100
	v_fma_f32 v109, v159, v109, -v101
	v_fma_f32 v218, v159, v218, -v102
	v_fma_f32 v219, v159, v219, -v103
	v_fma_f32 v220, v159, v220, -v104
	v_fma_f32 v221, v159, v221, -v105
	v_cvt_pk_bf16_f32 v106, v106, v107
	v_cvt_pk_bf16_f32 v107, v108, v109
	v_cvt_pk_bf16_f32 v108, v218, v219
	v_cvt_pk_bf16_f32 v109, v220, v221
	s_and_saveexec_b64 s[28:29], s[6:7]
	s_cbranch_execz .Lpu0_4
	global_store_dwordx4 v[192:193], v[98:101], off offset:256
	global_store_dwordx4 v[192:193], v[102:105], off offset:272
.Lpu0_4:
	s_or_b64 exec, exec, s[28:29]
	s_waitcnt vmcnt(8)
	v_mfma_f32_32x32x16_bf16 v[2:17], v[106:109], v[82:85], v[2:17]
	v_mfma_f32_32x32x16_bf16 v[18:33], v[106:109], v[86:89], v[18:33]
	v_mfma_f32_32x32x16_bf16 v[34:49], v[106:109], v[90:93], v[34:49]
	v_mfma_f32_32x32x16_bf16 v[50:65], v[106:109], v[94:97], v[50:65]
	global_load_dwordx4 v[82:85], v[144:145], off offset:3584
	global_load_dwordx4 v[86:89], v[146:147], off offset:3584
	global_load_dwordx4 v[90:93], v[148:149], off offset:3584
	global_load_dwordx4 v[94:97], v[150:151], off offset:3584
	s_waitcnt lgkmcnt(7)
	v_lshlrev_b32_e32 v98, 16, v222
	v_and_b32_e32 v99, 0xffff0000, v222
	v_lshlrev_b32_e32 v100, 16, v223
	v_and_b32_e32 v101, 0xffff0000, v223
	v_lshlrev_b32_e32 v102, 16, v224
	v_and_b32_e32 v103, 0xffff0000, v224
	v_lshlrev_b32_e32 v104, 16, v225
	v_and_b32_e32 v105, 0xffff0000, v225
	v_mov_b64_e32 v[106:107], v[98:99]
	v_mov_b64_e32 v[108:109], v[100:101]
	v_mov_b64_e32 v[218:219], v[102:103]
	v_mov_b64_e32 v[220:221], v[104:105]
	ds_read_b128 v[222:225], v163 offset:2064
	s_waitcnt lgkmcnt(7)
	v_dot2c_f32_bf16 v106, s50, v226
	v_dot2c_f32_bf16 v107, s51, v226
	v_dot2c_f32_bf16 v108, s50, v227
	v_dot2c_f32_bf16 v109, s51, v227
	v_dot2c_f32_bf16 v218, s50, v228
	v_dot2c_f32_bf16 v219, s51, v228
	v_dot2c_f32_bf16 v220, s50, v229
	v_dot2c_f32_bf16 v221, s51, v229
	ds_read_b128 v[226:229], v163 offset:1792
	s_waitcnt lgkmcnt(7)
	v_dot2c_f32_bf16 v106, s50, v230
	v_dot2c_f32_bf16 v107, s51, v230
	v_dot2c_f32_bf16 v108, s50, v231
	v_dot2c_f32_bf16 v109, s51, v231
	v_dot2c_f32_bf16 v218, s50, v232
	v_dot2c_f32_bf16 v219, s51, v232
	v_dot2c_f32_bf16 v220, s50, v233
	v_dot2c_f32_bf16 v221, s51, v233
	ds_read_b128 v[230:233], v163 offset:1520
	s_waitcnt lgkmcnt(7)
	v_dot2c_f32_bf16 v106, s50, v234
	v_dot2c_f32_bf16 v107, s51, v234
	v_dot2c_f32_bf16 v108, s50, v235
	v_dot2c_f32_bf16 v109, s51, v235
	v_dot2c_f32_bf16 v218, s50, v236
	v_dot2c_f32_bf16 v219, s51, v236
	v_dot2c_f32_bf16 v220, s50, v237
	v_dot2c_f32_bf16 v221, s51, v237
	ds_read_b128 v[234:237], v163 offset:1248
	s_waitcnt lgkmcnt(7)
	v_dot2c_f32_bf16 v106, s50, v238
	v_dot2c_f32_bf16 v107, s51, v238
	v_dot2c_f32_bf16 v108, s50, v239
	v_dot2c_f32_bf16 v109, s51, v239
	v_dot2c_f32_bf16 v218, s50, v240
	v_dot2c_f32_bf16 v219, s51, v240
	v_dot2c_f32_bf16 v220, s50, v241
	v_dot2c_f32_bf16 v221, s51, v241
	ds_read_b128 v[238:241], v163 offset:976
	s_waitcnt lgkmcnt(7)
	v_dot2c_f32_bf16 v106, s50, v242
	v_dot2c_f32_bf16 v107, s51, v242
	v_dot2c_f32_bf16 v108, s50, v243
	v_dot2c_f32_bf16 v109, s51, v243
	v_dot2c_f32_bf16 v218, s50, v244
	v_dot2c_f32_bf16 v219, s51, v244
	v_dot2c_f32_bf16 v220, s50, v245
	v_dot2c_f32_bf16 v221, s51, v245
	ds_read_b128 v[242:245], v163 offset:704
	s_waitcnt lgkmcnt(7)
	v_dot2c_f32_bf16 v106, s50, v248
	v_dot2c_f32_bf16 v107, s51, v248
	v_dot2c_f32_bf16 v108, s50, v249
	v_dot2c_f32_bf16 v109, s51, v249
	v_dot2c_f32_bf16 v218, s50, v250
	v_dot2c_f32_bf16 v219, s51, v250
	v_dot2c_f32_bf16 v220, s50, v251
	v_dot2c_f32_bf16 v221, s51, v251
	ds_read_b128 v[248:251], v163 offset:432
	s_waitcnt lgkmcnt(7)
	v_dot2c_f32_bf16 v106, s50, v252
	v_dot2c_f32_bf16 v107, s51, v252
	v_dot2c_f32_bf16 v108, s50, v253
	v_dot2c_f32_bf16 v109, s51, v253
	v_dot2c_f32_bf16 v218, s50, v254
	v_dot2c_f32_bf16 v219, s51, v254
	v_dot2c_f32_bf16 v220, s50, v255
	v_dot2c_f32_bf16 v221, s51, v255
	ds_read_b128 v[252:255], v163 offset:160
	s_waitcnt lgkmcnt(7)
	v_dot2c_f32_bf16 v106, s50, v222
	v_dot2c_f32_bf16 v107, s51, v222
	v_dot2c_f32_bf16 v108, s50, v223
	v_dot2c_f32_bf16 v109, s51, v223
	v_dot2c_f32_bf16 v218, s50, v224
	v_dot2c_f32_bf16 v219, s51, v224
	v_dot2c_f32_bf16 v220, s50, v225
	v_dot2c_f32_bf16 v221, s51, v225
	ds_read_b128 v[222:225], v163 offset:4272
	s_waitcnt lgkmcnt(7)
	v_dot2c_f32_bf16 v106, s50, v226
	v_dot2c_f32_bf16 v107, s51, v226
	v_dot2c_f32_bf16 v108, s50, v227
	v_dot2c_f32_bf16 v109, s51, v227
	v_dot2c_f32_bf16 v218, s50, v228
	v_dot2c_f32_bf16 v219, s51, v228
	v_dot2c_f32_bf16 v220, s50, v229
	v_dot2c_f32_bf16 v221, s51, v229
	ds_read_b128 v[226:229], v163 offset:4000
	s_waitcnt lgkmcnt(7)
	v_dot2c_f32_bf16 v106, s50, v230
	v_dot2c_f32_bf16 v107, s51, v230
	v_dot2c_f32_bf16 v108, s50, v231
	v_dot2c_f32_bf16 v109, s51, v231
	v_dot2c_f32_bf16 v218, s50, v232
	v_dot2c_f32_bf16 v219, s51, v232
	v_dot2c_f32_bf16 v220, s50, v233
	v_dot2c_f32_bf16 v221, s51, v233
	ds_read_b128 v[230:233], v163 offset:3728
	s_waitcnt lgkmcnt(7)
	v_dot2c_f32_bf16 v106, s50, v234
	v_dot2c_f32_bf16 v107, s51, v234
	v_dot2c_f32_bf16 v108, s50, v235
	v_dot2c_f32_bf16 v109, s51, v235
	v_dot2c_f32_bf16 v218, s50, v236
	v_dot2c_f32_bf16 v219, s51, v236
	v_dot2c_f32_bf16 v220, s50, v237
	v_dot2c_f32_bf16 v221, s51, v237
	ds_read_b128 v[234:237], v163 offset:3456
	s_waitcnt lgkmcnt(7)
	v_dot2c_f32_bf16 v106, s50, v238
	v_dot2c_f32_bf16 v107, s51, v238
	v_dot2c_f32_bf16 v108, s50, v239
	v_dot2c_f32_bf16 v109, s51, v239
	v_dot2c_f32_bf16 v218, s50, v240
	v_dot2c_f32_bf16 v219, s51, v240
	v_dot2c_f32_bf16 v220, s50, v241
	v_dot2c_f32_bf16 v221, s51, v241
	ds_read_b128 v[238:241], v163 offset:3184
	s_waitcnt lgkmcnt(7)
	v_dot2c_f32_bf16 v106, s50, v242
	v_dot2c_f32_bf16 v107, s51, v242
	v_dot2c_f32_bf16 v108, s50, v243
	v_dot2c_f32_bf16 v109, s51, v243
	v_dot2c_f32_bf16 v218, s50, v244
	v_dot2c_f32_bf16 v219, s51, v244
	v_dot2c_f32_bf16 v220, s50, v245
	v_dot2c_f32_bf16 v221, s51, v245
	ds_read_b128 v[242:245], v163 offset:2912
	s_waitcnt lgkmcnt(7)
	v_dot2c_f32_bf16 v106, s50, v248
	v_dot2c_f32_bf16 v107, s51, v248
	v_dot2c_f32_bf16 v108, s50, v249
	v_dot2c_f32_bf16 v109, s51, v249
	v_dot2c_f32_bf16 v218, s50, v250
	v_dot2c_f32_bf16 v219, s51, v250
	v_dot2c_f32_bf16 v220, s50, v251
	v_dot2c_f32_bf16 v221, s51, v251
	ds_read_b128 v[248:251], v163 offset:2640
	s_waitcnt lgkmcnt(7)
	v_dot2c_f32_bf16 v106, s50, v252
	v_dot2c_f32_bf16 v107, s51, v252
	v_dot2c_f32_bf16 v108, s50, v253
	v_dot2c_f32_bf16 v109, s51, v253
	v_dot2c_f32_bf16 v218, s50, v254
	v_dot2c_f32_bf16 v219, s51, v254
	v_dot2c_f32_bf16 v220, s50, v255
	v_dot2c_f32_bf16 v221, s51, v255
	ds_read_b128 v[252:255], v163 offset:2368
	v_fma_f32 v106, v159, v106, -v98
	v_fma_f32 v107, v159, v107, -v99
	v_fma_f32 v108, v159, v108, -v100
	v_fma_f32 v109, v159, v109, -v101
	v_fma_f32 v218, v159, v218, -v102
	v_fma_f32 v219, v159, v219, -v103
	v_fma_f32 v220, v159, v220, -v104
	v_fma_f32 v221, v159, v221, -v105
	v_cvt_pk_bf16_f32 v106, v106, v107
	v_cvt_pk_bf16_f32 v107, v108, v109
	v_cvt_pk_bf16_f32 v108, v218, v219
	v_cvt_pk_bf16_f32 v109, v220, v221
	s_and_saveexec_b64 s[28:29], s[6:7]
	s_cbranch_execz .Lpu0_5
	global_store_dwordx4 v[192:193], v[98:101], off offset:320
	global_store_dwordx4 v[192:193], v[102:105], off offset:336
.Lpu0_5:
	s_or_b64 exec, exec, s[28:29]
	s_waitcnt vmcnt(8)
	v_mfma_f32_32x32x16_bf16 v[2:17], v[106:109], v[112:115], v[2:17]
	v_mfma_f32_32x32x16_bf16 v[18:33], v[106:109], v[116:119], v[18:33]
	v_mfma_f32_32x32x16_bf16 v[34:49], v[106:109], v[122:125], v[34:49]
	v_mfma_f32_32x32x16_bf16 v[50:65], v[106:109], v[126:129], v[50:65]
	s_waitcnt lgkmcnt(7)
	v_lshlrev_b32_e32 v98, 16, v222
	v_and_b32_e32 v99, 0xffff0000, v222
	v_lshlrev_b32_e32 v100, 16, v223
	v_and_b32_e32 v101, 0xffff0000, v223
	v_lshlrev_b32_e32 v102, 16, v224
	v_and_b32_e32 v103, 0xffff0000, v224
	v_lshlrev_b32_e32 v104, 16, v225
	v_and_b32_e32 v105, 0xffff0000, v225
	v_mov_b64_e32 v[106:107], v[98:99]
	v_mov_b64_e32 v[108:109], v[100:101]
	v_mov_b64_e32 v[218:219], v[102:103]
	v_mov_b64_e32 v[220:221], v[104:105]
	ds_read_b128 v[222:225], v163 offset:2096
	s_waitcnt lgkmcnt(7)
	v_dot2c_f32_bf16 v106, s50, v226
	v_dot2c_f32_bf16 v107, s51, v226
	v_dot2c_f32_bf16 v108, s50, v227
	v_dot2c_f32_bf16 v109, s51, v227
	v_dot2c_f32_bf16 v218, s50, v228
	v_dot2c_f32_bf16 v219, s51, v228
	v_dot2c_f32_bf16 v220, s50, v229
	v_dot2c_f32_bf16 v221, s51, v229
	ds_read_b128 v[226:229], v163 offset:1824
	s_waitcnt lgkmcnt(7)
	v_dot2c_f32_bf16 v106, s50, v230
	v_dot2c_f32_bf16 v107, s51, v230
	v_dot2c_f32_bf16 v108, s50, v231
	v_dot2c_f32_bf16 v109, s51, v231
	v_dot2c_f32_bf16 v218, s50, v232
	v_dot2c_f32_bf16 v219, s51, v232
	v_dot2c_f32_bf16 v220, s50, v233
	v_dot2c_f32_bf16 v221, s51, v233
	ds_read_b128 v[230:233], v163 offset:1552
	s_waitcnt lgkmcnt(7)
	v_dot2c_f32_bf16 v106, s50, v234
	v_dot2c_f32_bf16 v107, s51, v234
	v_dot2c_f32_bf16 v108, s50, v235
	v_dot2c_f32_bf16 v109, s51, v235
	v_dot2c_f32_bf16 v218, s50, v236
	v_dot2c_f32_bf16 v219, s51, v236
	v_dot2c_f32_bf16 v220, s50, v237
	v_dot2c_f32_bf16 v221, s51, v237
	ds_read_b128 v[234:237], v163 offset:1280
	s_waitcnt lgkmcnt(7)
	v_dot2c_f32_bf16 v106, s50, v238
	v_dot2c_f32_bf16 v107, s51, v238
	v_dot2c_f32_bf16 v108, s50, v239
	v_dot2c_f32_bf16 v109, s51, v239
	v_dot2c_f32_bf16 v218, s50, v240
	v_dot2c_f32_bf16 v219, s51, v240
	v_dot2c_f32_bf16 v220, s50, v241
	v_dot2c_f32_bf16 v221, s51, v241
	ds_read_b128 v[238:241], v163 offset:1008
	s_waitcnt lgkmcnt(7)
	v_dot2c_f32_bf16 v106, s50, v242
	v_dot2c_f32_bf16 v107, s51, v242
	v_dot2c_f32_bf16 v108, s50, v243
	v_dot2c_f32_bf16 v109, s51, v243
	v_dot2c_f32_bf16 v218, s50, v244
	v_dot2c_f32_bf16 v219, s51, v244
	v_dot2c_f32_bf16 v220, s50, v245
	v_dot2c_f32_bf16 v221, s51, v245
	ds_read_b128 v[242:245], v163 offset:736
	s_waitcnt lgkmcnt(7)
	v_dot2c_f32_bf16 v106, s50, v248
	v_dot2c_f32_bf16 v107, s51, v248
	v_dot2c_f32_bf16 v108, s50, v249
	v_dot2c_f32_bf16 v109, s51, v249
	v_dot2c_f32_bf16 v218, s50, v250
	v_dot2c_f32_bf16 v219, s51, v250
	v_dot2c_f32_bf16 v220, s50, v251
	v_dot2c_f32_bf16 v221, s51, v251
	ds_read_b128 v[248:251], v163 offset:464
	s_waitcnt lgkmcnt(7)
	v_dot2c_f32_bf16 v106, s50, v252
	v_dot2c_f32_bf16 v107, s51, v252
	v_dot2c_f32_bf16 v108, s50, v253
	v_dot2c_f32_bf16 v109, s51, v253
	v_dot2c_f32_bf16 v218, s50, v254
	v_dot2c_f32_bf16 v219, s51, v254
	v_dot2c_f32_bf16 v220, s50, v255
	v_dot2c_f32_bf16 v221, s51, v255
	ds_read_b128 v[252:255], v163 offset:192
	s_waitcnt lgkmcnt(7)
	v_dot2c_f32_bf16 v106, s50, v222
	v_dot2c_f32_bf16 v107, s51, v222
	v_dot2c_f32_bf16 v108, s50, v223
	v_dot2c_f32_bf16 v109, s51, v223
	v_dot2c_f32_bf16 v218, s50, v224
	v_dot2c_f32_bf16 v219, s51, v224
	v_dot2c_f32_bf16 v220, s50, v225
	v_dot2c_f32_bf16 v221, s51, v225
	ds_read_b128 v[222:225], v163 offset:4304
	s_waitcnt lgkmcnt(7)
	v_dot2c_f32_bf16 v106, s50, v226
	v_dot2c_f32_bf16 v107, s51, v226
	v_dot2c_f32_bf16 v108, s50, v227
	v_dot2c_f32_bf16 v109, s51, v227
	v_dot2c_f32_bf16 v218, s50, v228
	v_dot2c_f32_bf16 v219, s51, v228
	v_dot2c_f32_bf16 v220, s50, v229
	v_dot2c_f32_bf16 v221, s51, v229
	ds_read_b128 v[226:229], v163 offset:4032
	s_waitcnt lgkmcnt(7)
	v_dot2c_f32_bf16 v106, s50, v230
	v_dot2c_f32_bf16 v107, s51, v230
	v_dot2c_f32_bf16 v108, s50, v231
	v_dot2c_f32_bf16 v109, s51, v231
	v_dot2c_f32_bf16 v218, s50, v232
	v_dot2c_f32_bf16 v219, s51, v232
	v_dot2c_f32_bf16 v220, s50, v233
	v_dot2c_f32_bf16 v221, s51, v233
	ds_read_b128 v[230:233], v163 offset:3760
	s_waitcnt lgkmcnt(7)
	v_dot2c_f32_bf16 v106, s50, v234
	v_dot2c_f32_bf16 v107, s51, v234
	v_dot2c_f32_bf16 v108, s50, v235
	v_dot2c_f32_bf16 v109, s51, v235
	v_dot2c_f32_bf16 v218, s50, v236
	v_dot2c_f32_bf16 v219, s51, v236
	v_dot2c_f32_bf16 v220, s50, v237
	v_dot2c_f32_bf16 v221, s51, v237
	ds_read_b128 v[234:237], v163 offset:3488
	s_waitcnt lgkmcnt(7)
	v_dot2c_f32_bf16 v106, s50, v238
	v_dot2c_f32_bf16 v107, s51, v238
	v_dot2c_f32_bf16 v108, s50, v239
	v_dot2c_f32_bf16 v109, s51, v239
	v_dot2c_f32_bf16 v218, s50, v240
	v_dot2c_f32_bf16 v219, s51, v240
	v_dot2c_f32_bf16 v220, s50, v241
	v_dot2c_f32_bf16 v221, s51, v241
	ds_read_b128 v[238:241], v163 offset:3216
	s_waitcnt lgkmcnt(7)
	v_dot2c_f32_bf16 v106, s50, v242
	v_dot2c_f32_bf16 v107, s51, v242
	v_dot2c_f32_bf16 v108, s50, v243
	v_dot2c_f32_bf16 v109, s51, v243
	v_dot2c_f32_bf16 v218, s50, v244
	v_dot2c_f32_bf16 v219, s51, v244
	v_dot2c_f32_bf16 v220, s50, v245
	v_dot2c_f32_bf16 v221, s51, v245
	ds_read_b128 v[242:245], v163 offset:2944
	s_waitcnt lgkmcnt(7)
	v_dot2c_f32_bf16 v106, s50, v248
	v_dot2c_f32_bf16 v107, s51, v248
	v_dot2c_f32_bf16 v108, s50, v249
	v_dot2c_f32_bf16 v109, s51, v249
	v_dot2c_f32_bf16 v218, s50, v250
	v_dot2c_f32_bf16 v219, s51, v250
	v_dot2c_f32_bf16 v220, s50, v251
	v_dot2c_f32_bf16 v221, s51, v251
	ds_read_b128 v[248:251], v163 offset:2672
	s_waitcnt lgkmcnt(7)
	v_dot2c_f32_bf16 v106, s50, v252
	v_dot2c_f32_bf16 v107, s51, v252
	v_dot2c_f32_bf16 v108, s50, v253
	v_dot2c_f32_bf16 v109, s51, v253
	v_dot2c_f32_bf16 v218, s50, v254
	v_dot2c_f32_bf16 v219, s51, v254
	v_dot2c_f32_bf16 v220, s50, v255
	v_dot2c_f32_bf16 v221, s51, v255
	ds_read_b128 v[252:255], v163 offset:2400
	v_fma_f32 v106, v159, v106, -v98
	v_fma_f32 v107, v159, v107, -v99
	v_fma_f32 v108, v159, v108, -v100
	v_fma_f32 v109, v159, v109, -v101
	v_fma_f32 v218, v159, v218, -v102
	v_fma_f32 v219, v159, v219, -v103
	v_fma_f32 v220, v159, v220, -v104
	v_fma_f32 v221, v159, v221, -v105
	v_cvt_pk_bf16_f32 v106, v106, v107
	v_cvt_pk_bf16_f32 v107, v108, v109
	v_cvt_pk_bf16_f32 v108, v218, v219
	v_cvt_pk_bf16_f32 v109, v220, v221
	s_and_saveexec_b64 s[28:29], s[6:7]
	s_cbranch_execz .Lpu0_6
	global_store_dwordx4 v[192:193], v[98:101], off offset:384
	global_store_dwordx4 v[192:193], v[102:105], off offset:400

.Lpu0_7:
	s_or_b64 exec, exec, s[28:29]
	s_waitcnt vmcnt(0)
	v_mfma_f32_32x32x16_bf16 v[2:17], v[106:109], v[82:85], v[2:17]
	v_mfma_f32_32x32x16_bf16 v[18:33], v[106:109], v[86:89], v[18:33]
	v_mfma_f32_32x32x16_bf16 v[34:49], v[106:109], v[90:93], v[34:49]
	v_mfma_f32_32x32x16_bf16 v[50:65], v[106:109], v[94:97], v[50:65]
	s_mov_b64 s[10:11], 0x10000
	v_lshl_add_u64 v[112:113], v[110:111], 0, s[10:11]
	s_mov_b64 s[10:11], 0x12000
	v_lshl_add_u64 v[114:115], v[110:111], 0, s[10:11]
	s_mov_b64 s[10:11], 0x14000
	v_lshl_add_u64 v[116:117], v[110:111], 0, s[10:11]
	s_mov_b64 s[10:11], 0x16000
	v_lshl_add_u64 v[118:119], v[110:111], 0, s[10:11]
	s_mov_b64 s[10:11], 0x8000
	v_lshl_add_u64 v[122:123], v[110:111], 0, s[10:11]
	s_mov_b64 s[10:11], 0xa000
	v_lshl_add_u64 v[124:125], v[110:111], 0, s[10:11]
	s_mov_b64 s[10:11], 0xc000
	v_lshl_add_u64 v[126:127], v[110:111], 0, s[10:11]
	s_mov_b64 s[10:11], 0xe000
	v_lshl_add_u64 v[128:129], v[110:111], 0, s[10:11]
	s_branch .LBB0_338
